# GDN (vi): sign flips folded into the bf16 pack conversions (neg source modifiers), 16 v_xor per stage removed
# baseline (speedup 1.0000x reference)
; #define LAS __attribute__((address_space(3)))
; #define LDS_WAIT() asm volatile("s_waitcnt lgkmcnt(0)" ::: "memory")
; #define LDS_BARRIER() do { asm volatile("s_waitcnt lgkmcnt(0)" ::: "memory"); __builtin_amdgcn_s_barrier(); asm volatile("" ::: "memory"); } while (0)
; __device__ __forceinline__ unsigned pk2(float lo, float hi) { const f32x2_t v = {lo, hi}; return __builtin_bit_cast(unsigned, __builtin_convertvector(v, bf16x2_t)); }
; #define MFMA16(a, b, c) __builtin_amdgcn_mfma_f32_16x16x32_bf16((a), (b), (c), 0, 0, 0)
; __device__ __forceinline__ void phase_gdn2(Frame& F, bool ctx_out, bool dry = false) {
;     ...
;                 f32x4 U[4];
; #pragma unroll
;                 for (int I = 0; I < 4; ++I) {
;                     const hb8 fa = *(const LAS hb8*)(TUB + (I * 16 + l15) * GB + q4 * 8), fb = *(const LAS hb8*)(VT + (vb * 16 + l15) * GT + I * 16 + q4 * 8);
;                     U[I] = MFMA16(fa, fb, ((f32x4){0.f, 0.f, 0.f, 0.f}));
;                     const hb8 ga = *(const LAS hb8*)(KCT + (vb * 16 + l15) * GT + I * 16 + q4 * 8), gbv = *(const LAS hb8*)(TWB + (I * 16 + l15) * GB + q4 * 8);
;                     const f32x4 wt = MFMA16(ga, gbv, ((f32x4){0.f, 0.f, 0.f, 0.f}));
;                     *(LAS v2u*)(W + (I * 16 + l15) * GS + vb * 16 + q4 * 4) = (v2u){pk2(-wt.x, -wt.y), pk2(-wt.z, -wt.w)};
;                 }
;                 LDS_WAIT(); asm volatile("" ::: "memory");
;                 LDS_BARRIER();
; #pragma unroll
;                 for (int I = 0; I < 4; ++I) {
;                     f32x4 vn = U[I], oa = (f32x4){0.f, 0.f, 0.f, 0.f};
; #pragma unroll
;                     for (int ks = 0; ks < 4; ++ks) {
;                         const v4u sb4 = (v4u){pk2(S[2 * ks].x, S[2 * ks].y), pk2(S[2 * ks].z, S[2 * ks].w), pk2(S[2 * ks + 1].x, S[2 * ks + 1].y), pk2(S[2 * ks + 1].z, S[2 * ks + 1].w)};
;                         const hb8 fb = __builtin_bit_cast(hb8, sb4);
;                         const v2u w0 = *(const LAS v2u*)(W + (I * 16 + l15) * GS + ks * 32 + q4 * 4), w1 = *(const LAS v2u*)(W + (I * 16 + l15) * GS + ks * 32 + 16 + q4 * 4);
.Lgdn_drained:
	v_add3_u32 v88, s0, v0, v1
	v_add3_u32 v89, s47, v0, v1
	ds_read_b128 v[154:157], v88
	ds_read_b128 v[158:161], v3 offset:55296
	ds_read_b128 v[162:165], v3 offset:34816
	ds_read_b128 v[166:169], v89
	ds_read_b128 v[170:173], v88 offset:1280
	ds_read_b128 v[174:177], v3 offset:55328
	ds_read_b128 v[178:181], v3 offset:34848
	ds_read_b128 v[182:185], v89 offset:1280
	ds_read_b128 v[186:189], v88 offset:2560
	ds_read_b128 v[190:193], v3 offset:55360
	ds_read_b128 v[194:197], v3 offset:34880
	ds_read_b128 v[198:201], v89 offset:2560
	ds_read_b128 v[202:205], v88 offset:3840
	ds_read_b128 v[206:209], v3 offset:55392
	ds_read_b128 v[210:213], v3 offset:34912
	ds_read_b128 v[214:217], v89 offset:3840
	v_add_u32_e32 v108, 0, v139
	v_add_u32_e32 v107, s76, v140
	v_add_u32_e32 v101, s85, v139
	v_mul_u32_u24_e32 v84, 0x110, v137
	v_add3_u32 v92, s67, v139, v84
	v_mad_u32_u24 v103, v137, s10, v108
	v_or_b32_e32 v110, 16, v137
	v_mad_u32_u24 v104, v110, s10, v108
	v_or_b32_e32 v109, 32, v137
	v_or_b32_e32 v100, 48, v137
	s_add_i32 s56, s56, 1
	s_add_i32 s3, s3, 64
	s_add_i32 s96, s96, 1
	s_cmpk_eq_i32 s3, 0x900
	s_waitcnt lgkmcnt(14)
	v_mfma_f32_16x16x32_bf16 v[68:71], v[154:157], v[158:161], 0
	s_waitcnt lgkmcnt(12)
	v_mfma_f32_16x16x32_bf16 v[218:221], v[162:165], v[166:169], 0
	s_waitcnt lgkmcnt(10)
	v_mfma_f32_16x16x32_bf16 v[80:83], v[170:173], v[174:177], 0
	s_waitcnt lgkmcnt(8)
	v_mfma_f32_16x16x32_bf16 v[222:225], v[178:181], v[182:185], 0
	s_waitcnt lgkmcnt(6)
	v_mfma_f32_16x16x32_bf16 v[76:79], v[186:189], v[190:193], 0
	s_waitcnt lgkmcnt(4)
	v_mfma_f32_16x16x32_bf16 v[226:229], v[194:197], v[198:201], 0
	s_waitcnt lgkmcnt(2)
	v_mfma_f32_16x16x32_bf16 v[72:75], v[202:205], v[206:209], 0
	s_waitcnt lgkmcnt(0)
	v_mfma_f32_16x16x32_bf16 v[230:233], v[210:213], v[214:217], 0
	v_cvt_pk_bf16_f32 v0, -v218, -v219
	v_cvt_pk_bf16_f32 v1, -v220, -v221
	ds_write_b64 v92, v[0:1]
	v_cvt_pk_bf16_f32 v0, -v222, -v223
	v_cvt_pk_bf16_f32 v1, -v224, -v225
	ds_write_b64 v92, v[0:1] offset:4352
	v_cvt_pk_bf16_f32 v0, -v226, -v227
	v_cvt_pk_bf16_f32 v1, -v228, -v229
	ds_write_b64 v92, v[0:1] offset:8704
	v_cvt_pk_bf16_f32 v0, -v230, -v231
	v_cvt_pk_bf16_f32 v1, -v232, -v233
	ds_write_b64 v92, v[0:1] offset:13056
	v_add_u32_e32 v0, 0, v140
	s_waitcnt lgkmcnt(0)
	v_add_u32_e32 v106, 0x24a80, v0
	v_add_u32_e32 v102, 0x24b80, v0
	v_mul_u32_u24_e32 v0, 0x88, v137
	v_lshl_add_u32 v0, v0, 1, v108
	s_waitcnt lgkmcnt(0)
	s_barrier
	v_mov_b32_e32 v218, 0
	v_mov_b32_e32 v219, 0
	v_mov_b32_e32 v234, 0
	v_mov_b32_e32 v235, 0
	v_mov_b32_e32 v242, 0
	v_mov_b32_e32 v243, 0
	v_mov_b32_e32 v246, 0
	v_mov_b32_e32 v247, 0
	v_mov_b32_e32 v250, s76
	ds_read_b128 v[236:239], v250 offset:768
	ds_read_b64 v[154:155], v0
	ds_read_b64 v[156:157], v0 offset:32
	ds_read_b64 v[170:171], v0 offset:17408
	ds_read_b64 v[172:173], v0 offset:17440
	ds_read_b64 v[158:159], v0 offset:64
	ds_read_b64 v[160:161], v0 offset:96
	ds_read_b64 v[174:175], v0 offset:17472
	ds_read_b64 v[176:177], v0 offset:17504
	v_mad_u32_u24 v252, v137, s84, v101
	v_lshlrev_b32_e32 v92, 1, v137
	v_mul_u32_u24_e32 v93, 0x440, v138
	v_add3_u32 v253, s89, v92, v93
	v_and_b32_e32 v92, 1, v137
	v_mul_u32_u24_e32 v93, 0x10e, v92
	v_add_u32_e32 v93, v253, v93
	v_mul_u32_u24_e32 v92, 6, v92
	v_perm_b32 v92, v92, v92, 0
	v_xor_b32_e32 v92, 0x5040100, v92
	v_cvt_pk_bf16_f32 v186, v36, v37
	v_cvt_pk_bf16_f32 v187, v38, v39
	v_cvt_pk_bf16_f32 v188, v40, v41
	v_cvt_pk_bf16_f32 v189, v42, v43
	ds_read_b64 v[162:163], v0 offset:128
	ds_read_b64 v[164:165], v0 offset:160
	ds_read_b64 v[178:179], v0 offset:17536
	ds_read_b64 v[180:181], v0 offset:17568
	s_waitcnt lgkmcnt(8)
	v_mfma_f32_16x16x32_bf16 v[68:71], v[154:157], v[186:189], v[68:71]
	v_mfma_f32_16x16x32_bf16 v[84:87], v[170:173], v[186:189], 0
	v_cvt_pk_bf16_f32 v190, v44, v45
	v_cvt_pk_bf16_f32 v191, v46, v47
	v_cvt_pk_bf16_f32 v192, v48, v49
	v_cvt_pk_bf16_f32 v193, v50, v51
	ds_read_b64 v[166:167], v0 offset:192
	ds_read_b64 v[168:169], v0 offset:224
	ds_read_b64 v[182:183], v0 offset:17600
	ds_read_b64 v[184:185], v0 offset:17632
	s_waitcnt lgkmcnt(8)
	v_mfma_f32_16x16x32_bf16 v[68:71], v[158:161], v[190:193], v[68:71]
	v_mfma_f32_16x16x32_bf16 v[84:87], v[174:177], v[190:193], v[84:87]
	v_cvt_pk_bf16_f32 v194, v52, v53
	v_cvt_pk_bf16_f32 v195, v54, v55
	v_cvt_pk_bf16_f32 v196, v56, v57
	v_cvt_pk_bf16_f32 v197, v58, v59
	ds_read_b64 v[202:203], v103 offset:34816
	ds_read_b64 v[204:205], v104 offset:34816
	ds_read_b64 v[206:207], v104 offset:37120
	ds_read_b64 v[208:209], v104 offset:39424
	s_waitcnt lgkmcnt(8)
	v_mfma_f32_16x16x32_bf16 v[68:71], v[162:165], v[194:197], v[68:71]
	v_mfma_f32_16x16x32_bf16 v[84:87], v[178:181], v[194:197], v[84:87]
	v_cvt_pk_bf16_f32 v198, v60, v61
	v_cvt_pk_bf16_f32 v199, v62, v63
	v_cvt_pk_bf16_f32 v200, v64, v65
	v_cvt_pk_bf16_f32 v201, v66, v67
	ds_read_b64 v[210:211], v103 offset:44032
	ds_read_b64 v[212:213], v103 offset:46336
	ds_read_b64 v[214:215], v103 offset:48640
	ds_read_b64 v[216:217], v103 offset:50944
	s_waitcnt lgkmcnt(8)
; #define LAS __attribute__((address_space(3)))
; __device__ __forceinline__ void phase_gdn2(Frame& F, bool ctx_out, bool dry = false) {
;     ...
;                 for (int I = 0; I < 4; ++I) {
;                     f32x4 vn = U[I], oa = (f32x4){0.f, 0.f, 0.f, 0.f};
; #pragma unroll
;                     for (int ks = 0; ks < 4; ++ks) {
;                         const v4u sb4 = (v4u){pk2(S[2 * ks].x, S[2 * ks].y), pk2(S[2 * ks].z, S[2 * ks].w), pk2(S[2 * ks + 1].x, S[2 * ks + 1].y), pk2(S[2 * ks + 1].z, S[2 * ks + 1].w)};
;                         const hb8 fb = __builtin_bit_cast(hb8, sb4);
;                         const v2u w0 = *(const LAS v2u*)(W + (I * 16 + l15) * GS + ks * 32 + q4 * 4), w1 = *(const LAS v2u*)(W + (I * 16 + l15) * GS + ks * 32 + 16 + q4 * 4);
;                         const v2u q0 = *(const LAS v2u*)(QC + (I * 16 + l15) * GS + ks * 32 + q4 * 4), q1 = *(const LAS v2u*)(QC + (I * 16 + l15) * GS + ks * 32 + 16 + q4 * 4);
;                         const v4u fw4 = (v4u){w0.x, w0.y, w1.x, w1.y}, fq4 = (v4u){q0.x, q0.y, q1.x, q1.y};
;                         vn = MFMA16(__builtin_bit_cast(hb8, fw4), fb, vn); oa = MFMA16(__builtin_bit_cast(hb8, fq4), fb, oa); }
;                     const f32x4 ck = *(const LAS f32x4*)(s_ckd + I * 16 + q4 * 4), eg = *(const LAS f32x4*)(s_eG + I * 16 + q4 * 4), rqv = *(const LAS f32x4*)(s_rq + I * 16 + q4 * 4);
;                     const v4u vn4 = (v4u){pk2(vn.x, vn.y), pk2(vn.z, vn.w), 0u, 0u}, vp4 = (v4u){pk2(vn.x * ck.x, vn.y * ck.y), pk2(vn.z * ck.z, vn.w * ck.w), 0u, 0u};
;                     oa = oa * eg;
;                     { const v2u a0 = *(const LAS v2u*)(QKB + (I * 16 + l15) * GB + q4 * 4); const v4u fa4 = (v4u){a0.x, a0.y, 0u, 0u}; oa = MFMA16(__builtin_bit_cast(hb8, fa4), __builtin_bit_cast(hb8, vn4), oa); }
;                     oa = oa * rqv;
; #pragma unroll
;                     for (int i = 0; i < 4; ++i) O16[(I * 16 + q4 * 4 + i) * GS + vb * 16 + l15] = (bf16)f2bf(oa[i]);
;                     const float ege = s_eGend[I];
;                     const hb8 fbn = __builtin_bit_cast(hb8, vp4);
; #pragma unroll
;                     for (int kt = 0; kt < 8; ++kt) { const v2u a0 = *(const LAS v2u*)(KCT + (kt * 16 + l15) * GT + I * 16 + q4 * 4); const v4u fa4 = (v4u){a0.x, a0.y, 0u, 0u}; S[kt] = MFMA16(__builtin_bit_cast(hb8, fa4), fbn, S[kt] * ege); }
	v_mfma_f32_16x16x32_bf16 v[68:71], v[166:169], v[198:201], v[68:71]
	v_mfma_f32_16x16x32_bf16 v[84:87], v[182:185], v[198:201], v[84:87]
	ds_read_b128 v[220:223], v106
	ds_read_b128 v[224:227], v107 offset:512
	ds_read_b128 v[228:231], v102
	ds_read_b64 v[232:233], v252
	v_pk_mul_f32 v[36:37], v[36:37], v[236:237] op_sel_hi:[1,0]
	v_pk_mul_f32 v[38:39], v[38:39], v[236:237] op_sel_hi:[1,0]
	v_pk_mul_f32 v[40:41], v[40:41], v[236:237] op_sel_hi:[1,0]
	v_pk_mul_f32 v[42:43], v[42:43], v[236:237] op_sel_hi:[1,0]
	v_pk_mul_f32 v[44:45], v[44:45], v[236:237] op_sel_hi:[1,0]
	v_pk_mul_f32 v[46:47], v[46:47], v[236:237] op_sel_hi:[1,0]
	v_pk_mul_f32 v[48:49], v[48:49], v[236:237] op_sel_hi:[1,0]
	v_pk_mul_f32 v[50:51], v[50:51], v[236:237] op_sel_hi:[1,0]
	v_pk_mul_f32 v[52:53], v[52:53], v[236:237] op_sel_hi:[1,0]
	v_pk_mul_f32 v[54:55], v[54:55], v[236:237] op_sel_hi:[1,0]
	v_pk_mul_f32 v[56:57], v[56:57], v[236:237] op_sel_hi:[1,0]
	v_pk_mul_f32 v[58:59], v[58:59], v[236:237] op_sel_hi:[1,0]
	v_pk_mul_f32 v[60:61], v[60:61], v[236:237] op_sel_hi:[1,0]
	v_pk_mul_f32 v[62:63], v[62:63], v[236:237] op_sel_hi:[1,0]
	v_pk_mul_f32 v[64:65], v[64:65], v[236:237] op_sel_hi:[1,0]
	v_pk_mul_f32 v[66:67], v[66:67], v[236:237] op_sel_hi:[1,0]
	s_waitcnt lgkmcnt(2)
	v_cvt_pk_bf16_f32 v240, v68, v69
	v_cvt_pk_bf16_f32 v241, v70, v71
	v_pk_mul_f32 v[88:89], v[68:69], v[220:221]
	v_pk_mul_f32 v[90:91], v[70:71], v[222:223]
	v_cvt_pk_bf16_f32 v244, v88, v89
	v_cvt_pk_bf16_f32 v245, v90, v91
	v_pk_mul_f32 v[84:85], v[84:85], v[224:225]
	v_pk_mul_f32 v[86:87], v[86:87], v[226:227]
	s_waitcnt lgkmcnt(0)
	v_mfma_f32_16x16x32_bf16 v[36:39], v[202:205], v[244:247], v[36:39]
	v_mfma_f32_16x16x32_bf16 v[40:43], v[204:207], v[244:247], v[40:43]
	v_mfma_f32_16x16x32_bf16 v[84:87], v[232:235], v[240:243], v[84:87]
	v_add_u32_e32 v250, 4352, v0
	v_mfma_f32_16x16x32_bf16 v[44:47], v[206:209], v[244:247], v[44:47]
	v_mfma_f32_16x16x32_bf16 v[48:51], v[208:211], v[244:247], v[48:51]
	v_mfma_f32_16x16x32_bf16 v[52:55], v[210:213], v[244:247], v[52:55]
	v_mfma_f32_16x16x32_bf16 v[56:59], v[212:215], v[244:247], v[56:59]
	v_mfma_f32_16x16x32_bf16 v[60:63], v[214:217], v[244:247], v[60:63]
	v_mfma_f32_16x16x32_bf16 v[64:67], v[216:219], v[244:247], v[64:67]
	ds_read_b64 v[154:155], v250
	ds_read_b64 v[156:157], v250 offset:32
	ds_read_b64 v[170:171], v250 offset:17408
	ds_read_b64 v[172:173], v250 offset:17440
	ds_read_b64 v[158:159], v250 offset:64
	ds_read_b64 v[160:161], v250 offset:96
	ds_read_b64 v[174:175], v250 offset:17472
	ds_read_b64 v[176:177], v250 offset:17504
	v_pk_mul_f32 v[84:85], v[84:85], v[228:229]
	v_pk_mul_f32 v[86:87], v[86:87], v[230:231]
	v_cvt_pk_bf16_f32 v88, v84, v85
	v_cvt_pk_bf16_f32 v90, v86, v87
	s_nop 1
	v_mov_b32_dpp v89, v88 quad_perm:[1,0,3,2] row_mask:0xf bank_mask:0xf
	v_mov_b32_dpp v91, v90 quad_perm:[1,0,3,2] row_mask:0xf bank_mask:0xf
	v_perm_b32 v88, v89, v88, v92
	v_perm_b32 v90, v91, v90, v92
	ds_write_b32 v93, v88
	ds_write_b32 v93, v90 offset:544
	v_cvt_pk_bf16_f32 v186, v36, v37
	v_cvt_pk_bf16_f32 v187, v38, v39
	v_cvt_pk_bf16_f32 v188, v40, v41
	v_cvt_pk_bf16_f32 v189, v42, v43
	s_waitcnt lgkmcnt(8)
	ds_read_b64 v[162:163], v250 offset:128
	ds_read_b64 v[164:165], v250 offset:160
	ds_read_b64 v[178:179], v250 offset:17536
	ds_read_b64 v[180:181], v250 offset:17568
	s_waitcnt lgkmcnt(8)
	v_mfma_f32_16x16x32_bf16 v[80:83], v[154:157], v[186:189], v[80:83]
	v_mfma_f32_16x16x32_bf16 v[84:87], v[170:173], v[186:189], 0
	v_cvt_pk_bf16_f32 v190, v44, v45
	v_cvt_pk_bf16_f32 v191, v46, v47
	v_cvt_pk_bf16_f32 v192, v48, v49
	v_cvt_pk_bf16_f32 v193, v50, v51
	ds_read_b64 v[166:167], v250 offset:192
	ds_read_b64 v[168:169], v250 offset:224
	ds_read_b64 v[182:183], v250 offset:17600
	ds_read_b64 v[184:185], v250 offset:17632
	s_waitcnt lgkmcnt(8)
	v_mfma_f32_16x16x32_bf16 v[80:83], v[158:161], v[190:193], v[80:83]
	v_mfma_f32_16x16x32_bf16 v[84:87], v[174:177], v[190:193], v[84:87]
	v_cvt_pk_bf16_f32 v194, v52, v53
	v_cvt_pk_bf16_f32 v195, v54, v55
	v_cvt_pk_bf16_f32 v196, v56, v57
	v_cvt_pk_bf16_f32 v197, v58, v59
	ds_read_b64 v[202:203], v103 offset:34848
	ds_read_b64 v[204:205], v104 offset:34848
	ds_read_b64 v[206:207], v104 offset:37152
	ds_read_b64 v[208:209], v104 offset:39456
	s_waitcnt lgkmcnt(8)
	v_mfma_f32_16x16x32_bf16 v[80:83], v[162:165], v[194:197], v[80:83]
	v_mfma_f32_16x16x32_bf16 v[84:87], v[178:181], v[194:197], v[84:87]
	v_cvt_pk_bf16_f32 v198, v60, v61
	v_cvt_pk_bf16_f32 v199, v62, v63
	v_cvt_pk_bf16_f32 v200, v64, v65
	v_cvt_pk_bf16_f32 v201, v66, v67
	ds_read_b64 v[210:211], v103 offset:44064
	ds_read_b64 v[212:213], v103 offset:46368
	ds_read_b64 v[214:215], v103 offset:48672
	ds_read_b64 v[216:217], v103 offset:50976
	s_waitcnt lgkmcnt(8)
	v_mfma_f32_16x16x32_bf16 v[80:83], v[166:169], v[198:201], v[80:83]
	v_mfma_f32_16x16x32_bf16 v[84:87], v[182:185], v[198:201], v[84:87]
	ds_read_b128 v[220:223], v106 offset:64
	ds_read_b128 v[224:227], v107 offset:576
	ds_read_b128 v[228:231], v102 offset:64
	ds_read_b64 v[232:233], v252 offset:1280
	v_pk_mul_f32 v[36:37], v[36:37], v[236:237] op_sel:[0,1]
	v_pk_mul_f32 v[38:39], v[38:39], v[236:237] op_sel:[0,1]
	v_pk_mul_f32 v[40:41], v[40:41], v[236:237] op_sel:[0,1]
	v_pk_mul_f32 v[42:43], v[42:43], v[236:237] op_sel:[0,1]
	v_pk_mul_f32 v[44:45], v[44:45], v[236:237] op_sel:[0,1]
	v_pk_mul_f32 v[46:47], v[46:47], v[236:237] op_sel:[0,1]
	v_pk_mul_f32 v[48:49], v[48:49], v[236:237] op_sel:[0,1]
	v_pk_mul_f32 v[50:51], v[50:51], v[236:237] op_sel:[0,1]
	v_pk_mul_f32 v[52:53], v[52:53], v[236:237] op_sel:[0,1]
	v_pk_mul_f32 v[54:55], v[54:55], v[236:237] op_sel:[0,1]
	v_pk_mul_f32 v[56:57], v[56:57], v[236:237] op_sel:[0,1]
	v_pk_mul_f32 v[58:59], v[58:59], v[236:237] op_sel:[0,1]
	v_pk_mul_f32 v[60:61], v[60:61], v[236:237] op_sel:[0,1]
	v_pk_mul_f32 v[62:63], v[62:63], v[236:237] op_sel:[0,1]
	v_pk_mul_f32 v[64:65], v[64:65], v[236:237] op_sel:[0,1]
	v_pk_mul_f32 v[66:67], v[66:67], v[236:237] op_sel:[0,1]
	s_waitcnt lgkmcnt(2)
; #define LAS __attribute__((address_space(3)))
; __device__ __forceinline__ void phase_gdn2(Frame& F, bool ctx_out, bool dry = false) {
;     ...
; #pragma unroll
;                 for (int I = 0; I < 4; ++I) {
;                     f32x4 vn = U[I], oa = (f32x4){0.f, 0.f, 0.f, 0.f};
; #pragma unroll
;                     for (int ks = 0; ks < 4; ++ks) {
;                         const v4u sb4 = (v4u){pk2(S[2 * ks].x, S[2 * ks].y), pk2(S[2 * ks].z, S[2 * ks].w), pk2(S[2 * ks + 1].x, S[2 * ks + 1].y), pk2(S[2 * ks + 1].z, S[2 * ks + 1].w)};
;                         const hb8 fb = __builtin_bit_cast(hb8, sb4);
;                         const v2u w0 = *(const LAS v2u*)(W + (I * 16 + l15) * GS + ks * 32 + q4 * 4), w1 = *(const LAS v2u*)(W + (I * 16 + l15) * GS + ks * 32 + 16 + q4 * 4);
;                         const v2u q0 = *(const LAS v2u*)(QC + (I * 16 + l15) * GS + ks * 32 + q4 * 4), q1 = *(const LAS v2u*)(QC + (I * 16 + l15) * GS + ks * 32 + 16 + q4 * 4);
;                         const v4u fw4 = (v4u){w0.x, w0.y, w1.x, w1.y}, fq4 = (v4u){q0.x, q0.y, q1.x, q1.y};
;                         vn = MFMA16(__builtin_bit_cast(hb8, fw4), fb, vn); oa = MFMA16(__builtin_bit_cast(hb8, fq4), fb, oa); }
;                     const f32x4 ck = *(const LAS f32x4*)(s_ckd + I * 16 + q4 * 4), eg = *(const LAS f32x4*)(s_eG + I * 16 + q4 * 4), rqv = *(const LAS f32x4*)(s_rq + I * 16 + q4 * 4);
;                     const v4u vn4 = (v4u){pk2(vn.x, vn.y), pk2(vn.z, vn.w), 0u, 0u}, vp4 = (v4u){pk2(vn.x * ck.x, vn.y * ck.y), pk2(vn.z * ck.z, vn.w * ck.w), 0u, 0u};
;                     oa = oa * eg;
;                     { const v2u a0 = *(const LAS v2u*)(QKB + (I * 16 + l15) * GB + q4 * 4); const v4u fa4 = (v4u){a0.x, a0.y, 0u, 0u}; oa = MFMA16(__builtin_bit_cast(hb8, fa4), __builtin_bit_cast(hb8, vn4), oa); }
;                     oa = oa * rqv;
; #pragma unroll
;                     for (int i = 0; i < 4; ++i) O16[(I * 16 + q4 * 4 + i) * GS + vb * 16 + l15] = (bf16)f2bf(oa[i]);
;                     const float ege = s_eGend[I];
;                     const hb8 fbn = __builtin_bit_cast(hb8, vp4);
; #pragma unroll
;                     for (int kt = 0; kt < 8; ++kt) { const v2u a0 = *(const LAS v2u*)(KCT + (kt * 16 + l15) * GT + I * 16 + q4 * 4); const v4u fa4 = (v4u){a0.x, a0.y, 0u, 0u}; S[kt] = MFMA16(__builtin_bit_cast(hb8, fa4), fbn, S[kt] * ege); }
;                 }
	v_cvt_pk_bf16_f32 v240, v80, v81
	v_cvt_pk_bf16_f32 v241, v82, v83
	v_pk_mul_f32 v[88:89], v[80:81], v[220:221]
	v_pk_mul_f32 v[90:91], v[82:83], v[222:223]
	v_cvt_pk_bf16_f32 v244, v88, v89
	v_cvt_pk_bf16_f32 v245, v90, v91
	v_pk_mul_f32 v[84:85], v[84:85], v[224:225]
	v_pk_mul_f32 v[86:87], v[86:87], v[226:227]
	s_waitcnt lgkmcnt(0)
	v_mfma_f32_16x16x32_bf16 v[36:39], v[202:205], v[244:247], v[36:39]
	v_mfma_f32_16x16x32_bf16 v[40:43], v[204:207], v[244:247], v[40:43]
	v_mfma_f32_16x16x32_bf16 v[84:87], v[232:235], v[240:243], v[84:87]
	v_add_u32_e32 v250, 8704, v0
	v_mfma_f32_16x16x32_bf16 v[44:47], v[206:209], v[244:247], v[44:47]
	v_mfma_f32_16x16x32_bf16 v[48:51], v[208:211], v[244:247], v[48:51]
	v_mfma_f32_16x16x32_bf16 v[52:55], v[210:213], v[244:247], v[52:55]
	v_mfma_f32_16x16x32_bf16 v[56:59], v[212:215], v[244:247], v[56:59]
	v_mfma_f32_16x16x32_bf16 v[60:63], v[214:217], v[244:247], v[60:63]
	v_mfma_f32_16x16x32_bf16 v[64:67], v[216:219], v[244:247], v[64:67]
	ds_read_b64 v[154:155], v250
	ds_read_b64 v[156:157], v250 offset:32
	ds_read_b64 v[170:171], v250 offset:17408
	ds_read_b64 v[172:173], v250 offset:17440
	ds_read_b64 v[158:159], v250 offset:64
	ds_read_b64 v[160:161], v250 offset:96
	ds_read_b64 v[174:175], v250 offset:17472
	ds_read_b64 v[176:177], v250 offset:17504
	v_pk_mul_f32 v[84:85], v[84:85], v[228:229]
	v_pk_mul_f32 v[86:87], v[86:87], v[230:231]
	v_cvt_pk_bf16_f32 v88, v84, v85
	v_cvt_pk_bf16_f32 v90, v86, v87
	s_nop 1
	v_mov_b32_dpp v89, v88 quad_perm:[1,0,3,2] row_mask:0xf bank_mask:0xf
	v_mov_b32_dpp v91, v90 quad_perm:[1,0,3,2] row_mask:0xf bank_mask:0xf
	v_perm_b32 v88, v89, v88, v92
	v_perm_b32 v90, v91, v90, v92
	ds_write_b32 v93, v88 offset:4352
	ds_write_b32 v93, v90 offset:4896
	v_cvt_pk_bf16_f32 v186, v36, v37
	v_cvt_pk_bf16_f32 v187, v38, v39
	v_cvt_pk_bf16_f32 v188, v40, v41
	v_cvt_pk_bf16_f32 v189, v42, v43
	s_waitcnt lgkmcnt(8)
	ds_read_b64 v[162:163], v250 offset:128
	ds_read_b64 v[164:165], v250 offset:160
	ds_read_b64 v[178:179], v250 offset:17536
	ds_read_b64 v[180:181], v250 offset:17568
	s_waitcnt lgkmcnt(8)
	v_mfma_f32_16x16x32_bf16 v[76:79], v[154:157], v[186:189], v[76:79]
	v_mfma_f32_16x16x32_bf16 v[84:87], v[170:173], v[186:189], 0
	v_cvt_pk_bf16_f32 v190, v44, v45
	v_cvt_pk_bf16_f32 v191, v46, v47
	v_cvt_pk_bf16_f32 v192, v48, v49
	v_cvt_pk_bf16_f32 v193, v50, v51
	ds_read_b64 v[166:167], v250 offset:192
	ds_read_b64 v[168:169], v250 offset:224
	ds_read_b64 v[182:183], v250 offset:17600
	ds_read_b64 v[184:185], v250 offset:17632
	s_waitcnt lgkmcnt(8)
	v_mfma_f32_16x16x32_bf16 v[76:79], v[158:161], v[190:193], v[76:79]
	v_mfma_f32_16x16x32_bf16 v[84:87], v[174:177], v[190:193], v[84:87]
	v_cvt_pk_bf16_f32 v194, v52, v53
	v_cvt_pk_bf16_f32 v195, v54, v55
	v_cvt_pk_bf16_f32 v196, v56, v57
	v_cvt_pk_bf16_f32 v197, v58, v59
	ds_read_b64 v[202:203], v103 offset:34880
	ds_read_b64 v[204:205], v104 offset:34880
	ds_read_b64 v[206:207], v104 offset:37184
	ds_read_b64 v[208:209], v104 offset:39488
	s_waitcnt lgkmcnt(8)
	v_mfma_f32_16x16x32_bf16 v[76:79], v[162:165], v[194:197], v[76:79]
	v_mfma_f32_16x16x32_bf16 v[84:87], v[178:181], v[194:197], v[84:87]
	v_cvt_pk_bf16_f32 v198, v60, v61
	v_cvt_pk_bf16_f32 v199, v62, v63
	v_cvt_pk_bf16_f32 v200, v64, v65
	v_cvt_pk_bf16_f32 v201, v66, v67
	ds_read_b64 v[210:211], v103 offset:44096
	ds_read_b64 v[212:213], v103 offset:46400
	ds_read_b64 v[214:215], v103 offset:48704
	ds_read_b64 v[216:217], v103 offset:51008
	s_waitcnt lgkmcnt(8)
	v_mfma_f32_16x16x32_bf16 v[76:79], v[166:169], v[198:201], v[76:79]
	v_mfma_f32_16x16x32_bf16 v[84:87], v[182:185], v[198:201], v[84:87]
	ds_read_b128 v[220:223], v106 offset:128
	ds_read_b128 v[224:227], v107 offset:640
	ds_read_b128 v[228:231], v102 offset:128
	ds_read_b64 v[232:233], v252 offset:2560
	v_pk_mul_f32 v[36:37], v[36:37], v[238:239] op_sel_hi:[1,0]
	v_pk_mul_f32 v[38:39], v[38:39], v[238:239] op_sel_hi:[1,0]
	v_pk_mul_f32 v[40:41], v[40:41], v[238:239] op_sel_hi:[1,0]
	v_pk_mul_f32 v[42:43], v[42:43], v[238:239] op_sel_hi:[1,0]
	v_pk_mul_f32 v[44:45], v[44:45], v[238:239] op_sel_hi:[1,0]
	v_pk_mul_f32 v[46:47], v[46:47], v[238:239] op_sel_hi:[1,0]
	v_pk_mul_f32 v[48:49], v[48:49], v[238:239] op_sel_hi:[1,0]
	v_pk_mul_f32 v[50:51], v[50:51], v[238:239] op_sel_hi:[1,0]
	v_pk_mul_f32 v[52:53], v[52:53], v[238:239] op_sel_hi:[1,0]
	v_pk_mul_f32 v[54:55], v[54:55], v[238:239] op_sel_hi:[1,0]
	v_pk_mul_f32 v[56:57], v[56:57], v[238:239] op_sel_hi:[1,0]
	v_pk_mul_f32 v[58:59], v[58:59], v[238:239] op_sel_hi:[1,0]
	v_pk_mul_f32 v[60:61], v[60:61], v[238:239] op_sel_hi:[1,0]
	v_pk_mul_f32 v[62:63], v[62:63], v[238:239] op_sel_hi:[1,0]
	v_pk_mul_f32 v[64:65], v[64:65], v[238:239] op_sel_hi:[1,0]
	v_pk_mul_f32 v[66:67], v[66:67], v[238:239] op_sel_hi:[1,0]
	s_waitcnt lgkmcnt(2)
	v_cvt_pk_bf16_f32 v240, v76, v77
	v_cvt_pk_bf16_f32 v241, v78, v79
	v_pk_mul_f32 v[88:89], v[76:77], v[220:221]
	v_pk_mul_f32 v[90:91], v[78:79], v[222:223]
	v_cvt_pk_bf16_f32 v244, v88, v89
	v_cvt_pk_bf16_f32 v245, v90, v91
	v_pk_mul_f32 v[84:85], v[84:85], v[224:225]
	v_pk_mul_f32 v[86:87], v[86:87], v[226:227]
	s_waitcnt lgkmcnt(0)
; __device__ __forceinline__ void phase_gdn2(Frame& F, bool ctx_out, bool dry = false) {
;     ...
; #pragma unroll
;                 for (int I = 0; I < 4; ++I) {
;                     f32x4 vn = U[I], oa = (f32x4){0.f, 0.f, 0.f, 0.f};
; #pragma unroll
;                     for (int ks = 0; ks < 4; ++ks) {
;                         const v4u sb4 = (v4u){pk2(S[2 * ks].x, S[2 * ks].y), pk2(S[2 * ks].z, S[2 * ks].w), pk2(S[2 * ks + 1].x, S[2 * ks + 1].y), pk2(S[2 * ks + 1].z, S[2 * ks + 1].w)};
;                         const hb8 fb = __builtin_bit_cast(hb8, sb4);
;                         const v2u w0 = *(const LAS v2u*)(W + (I * 16 + l15) * GS + ks * 32 + q4 * 4), w1 = *(const LAS v2u*)(W + (I * 16 + l15) * GS + ks * 32 + 16 + q4 * 4);
;                         const v2u q0 = *(const LAS v2u*)(QC + (I * 16 + l15) * GS + ks * 32 + q4 * 4), q1 = *(const LAS v2u*)(QC + (I * 16 + l15) * GS + ks * 32 + 16 + q4 * 4);
;                         const v4u fw4 = (v4u){w0.x, w0.y, w1.x, w1.y}, fq4 = (v4u){q0.x, q0.y, q1.x, q1.y};
;                         vn = MFMA16(__builtin_bit_cast(hb8, fw4), fb, vn); oa = MFMA16(__builtin_bit_cast(hb8, fq4), fb, oa); }
;                     const f32x4 ck = *(const LAS f32x4*)(s_ckd + I * 16 + q4 * 4), eg = *(const LAS f32x4*)(s_eG + I * 16 + q4 * 4), rqv = *(const LAS f32x4*)(s_rq + I * 16 + q4 * 4);
;                     const v4u vn4 = (v4u){pk2(vn.x, vn.y), pk2(vn.z, vn.w), 0u, 0u}, vp4 = (v4u){pk2(vn.x * ck.x, vn.y * ck.y), pk2(vn.z * ck.z, vn.w * ck.w), 0u, 0u};
;                     oa = oa * eg;
;                     { const v2u a0 = *(const LAS v2u*)(QKB + (I * 16 + l15) * GB + q4 * 4); const v4u fa4 = (v4u){a0.x, a0.y, 0u, 0u}; oa = MFMA16(__builtin_bit_cast(hb8, fa4), __builtin_bit_cast(hb8, vn4), oa); }
;                     oa = oa * rqv;
; #pragma unroll
;                     for (int i = 0; i < 4; ++i) O16[(I * 16 + q4 * 4 + i) * GS + vb * 16 + l15] = (bf16)f2bf(oa[i]);
;                     const float ege = s_eGend[I];
;                     const hb8 fbn = __builtin_bit_cast(hb8, vp4);
; #pragma unroll
;                     for (int kt = 0; kt < 8; ++kt) { const v2u a0 = *(const LAS v2u*)(KCT + (kt * 16 + l15) * GT + I * 16 + q4 * 4); const v4u fa4 = (v4u){a0.x, a0.y, 0u, 0u}; S[kt] = MFMA16(__builtin_bit_cast(hb8, fa4), fbn, S[kt] * ege); }
;                 }
;                 LDS_BARRIER();
	v_mfma_f32_16x16x32_bf16 v[36:39], v[202:205], v[244:247], v[36:39]
	v_mfma_f32_16x16x32_bf16 v[40:43], v[204:207], v[244:247], v[40:43]
	v_mfma_f32_16x16x32_bf16 v[84:87], v[232:235], v[240:243], v[84:87]
	v_add_u32_e32 v250, 13056, v0
	v_mfma_f32_16x16x32_bf16 v[44:47], v[206:209], v[244:247], v[44:47]
	v_mfma_f32_16x16x32_bf16 v[48:51], v[208:211], v[244:247], v[48:51]
	v_mfma_f32_16x16x32_bf16 v[52:55], v[210:213], v[244:247], v[52:55]
	v_mfma_f32_16x16x32_bf16 v[56:59], v[212:215], v[244:247], v[56:59]
	v_mfma_f32_16x16x32_bf16 v[60:63], v[214:217], v[244:247], v[60:63]
	v_mfma_f32_16x16x32_bf16 v[64:67], v[216:219], v[244:247], v[64:67]
	ds_read_b64 v[154:155], v250
	ds_read_b64 v[156:157], v250 offset:32
	ds_read_b64 v[170:171], v250 offset:17408
	ds_read_b64 v[172:173], v250 offset:17440
	ds_read_b64 v[158:159], v250 offset:64
	ds_read_b64 v[160:161], v250 offset:96
	ds_read_b64 v[174:175], v250 offset:17472
	ds_read_b64 v[176:177], v250 offset:17504
	v_pk_mul_f32 v[84:85], v[84:85], v[228:229]
	v_pk_mul_f32 v[86:87], v[86:87], v[230:231]
	v_cvt_pk_bf16_f32 v88, v84, v85
	v_cvt_pk_bf16_f32 v90, v86, v87
	s_nop 1
	v_mov_b32_dpp v89, v88 quad_perm:[1,0,3,2] row_mask:0xf bank_mask:0xf
	v_mov_b32_dpp v91, v90 quad_perm:[1,0,3,2] row_mask:0xf bank_mask:0xf
	v_perm_b32 v88, v89, v88, v92
	v_perm_b32 v90, v91, v90, v92
	ds_write_b32 v93, v88 offset:8704
	ds_write_b32 v93, v90 offset:9248
	v_cvt_pk_bf16_f32 v186, v36, v37
	v_cvt_pk_bf16_f32 v187, v38, v39
	v_cvt_pk_bf16_f32 v188, v40, v41
	v_cvt_pk_bf16_f32 v189, v42, v43
	s_waitcnt lgkmcnt(8)
	ds_read_b64 v[162:163], v250 offset:128
	ds_read_b64 v[164:165], v250 offset:160
	ds_read_b64 v[178:179], v250 offset:17536
	ds_read_b64 v[180:181], v250 offset:17568
	s_waitcnt lgkmcnt(8)
	v_mfma_f32_16x16x32_bf16 v[72:75], v[154:157], v[186:189], v[72:75]
	v_mfma_f32_16x16x32_bf16 v[84:87], v[170:173], v[186:189], 0
	v_cvt_pk_bf16_f32 v190, v44, v45
	v_cvt_pk_bf16_f32 v191, v46, v47
	v_cvt_pk_bf16_f32 v192, v48, v49
	v_cvt_pk_bf16_f32 v193, v50, v51
	ds_read_b64 v[166:167], v250 offset:192
	ds_read_b64 v[168:169], v250 offset:224
	ds_read_b64 v[182:183], v250 offset:17600
	ds_read_b64 v[184:185], v250 offset:17632
	s_waitcnt lgkmcnt(8)
	v_mfma_f32_16x16x32_bf16 v[72:75], v[158:161], v[190:193], v[72:75]
	v_mfma_f32_16x16x32_bf16 v[84:87], v[174:177], v[190:193], v[84:87]
	v_cvt_pk_bf16_f32 v194, v52, v53
	v_cvt_pk_bf16_f32 v195, v54, v55
	v_cvt_pk_bf16_f32 v196, v56, v57
	v_cvt_pk_bf16_f32 v197, v58, v59
	ds_read_b64 v[202:203], v103 offset:34912
	ds_read_b64 v[204:205], v104 offset:34912
	ds_read_b64 v[206:207], v104 offset:37216
	ds_read_b64 v[208:209], v104 offset:39520
	s_waitcnt lgkmcnt(8)
	v_mfma_f32_16x16x32_bf16 v[72:75], v[162:165], v[194:197], v[72:75]
	v_mfma_f32_16x16x32_bf16 v[84:87], v[178:181], v[194:197], v[84:87]
	v_cvt_pk_bf16_f32 v198, v60, v61
	v_cvt_pk_bf16_f32 v199, v62, v63
	v_cvt_pk_bf16_f32 v200, v64, v65
	v_cvt_pk_bf16_f32 v201, v66, v67
	ds_read_b64 v[210:211], v103 offset:44128
	ds_read_b64 v[212:213], v103 offset:46432
	ds_read_b64 v[214:215], v103 offset:48736
	ds_read_b64 v[216:217], v103 offset:51040
	s_waitcnt lgkmcnt(8)
	v_mfma_f32_16x16x32_bf16 v[72:75], v[166:169], v[198:201], v[72:75]
	v_mfma_f32_16x16x32_bf16 v[84:87], v[182:185], v[198:201], v[84:87]
	ds_read_b128 v[220:223], v106 offset:192
	ds_read_b128 v[224:227], v107 offset:704
	ds_read_b128 v[228:231], v102 offset:192
	ds_read_b64 v[232:233], v252 offset:3840
	v_pk_mul_f32 v[36:37], v[36:37], v[238:239] op_sel:[0,1]
	v_pk_mul_f32 v[38:39], v[38:39], v[238:239] op_sel:[0,1]
	v_pk_mul_f32 v[40:41], v[40:41], v[238:239] op_sel:[0,1]
	v_pk_mul_f32 v[42:43], v[42:43], v[238:239] op_sel:[0,1]
	v_pk_mul_f32 v[44:45], v[44:45], v[238:239] op_sel:[0,1]
	v_pk_mul_f32 v[46:47], v[46:47], v[238:239] op_sel:[0,1]
	v_pk_mul_f32 v[48:49], v[48:49], v[238:239] op_sel:[0,1]
	v_pk_mul_f32 v[50:51], v[50:51], v[238:239] op_sel:[0,1]
	v_pk_mul_f32 v[52:53], v[52:53], v[238:239] op_sel:[0,1]
	v_pk_mul_f32 v[54:55], v[54:55], v[238:239] op_sel:[0,1]
	v_pk_mul_f32 v[56:57], v[56:57], v[238:239] op_sel:[0,1]
	v_pk_mul_f32 v[58:59], v[58:59], v[238:239] op_sel:[0,1]
	v_pk_mul_f32 v[60:61], v[60:61], v[238:239] op_sel:[0,1]
	v_pk_mul_f32 v[62:63], v[62:63], v[238:239] op_sel:[0,1]
	v_pk_mul_f32 v[64:65], v[64:65], v[238:239] op_sel:[0,1]
	v_pk_mul_f32 v[66:67], v[66:67], v[238:239] op_sel:[0,1]
	s_waitcnt lgkmcnt(2)
	v_cvt_pk_bf16_f32 v240, v72, v73
	v_cvt_pk_bf16_f32 v241, v74, v75
	v_pk_mul_f32 v[88:89], v[72:73], v[220:221]
	v_pk_mul_f32 v[90:91], v[74:75], v[222:223]
	v_cvt_pk_bf16_f32 v244, v88, v89
	v_cvt_pk_bf16_f32 v245, v90, v91
	v_pk_mul_f32 v[84:85], v[84:85], v[224:225]
	v_pk_mul_f32 v[86:87], v[86:87], v[226:227]
	s_waitcnt lgkmcnt(0)
	v_mfma_f32_16x16x32_bf16 v[36:39], v[202:205], v[244:247], v[36:39]
	v_mfma_f32_16x16x32_bf16 v[40:43], v[204:207], v[244:247], v[40:43]
	v_mfma_f32_16x16x32_bf16 v[84:87], v[232:235], v[240:243], v[84:87]
	v_mfma_f32_16x16x32_bf16 v[44:47], v[206:209], v[244:247], v[44:47]
	v_mfma_f32_16x16x32_bf16 v[48:51], v[208:211], v[244:247], v[48:51]
	v_mfma_f32_16x16x32_bf16 v[52:55], v[210:213], v[244:247], v[52:55]
	v_mfma_f32_16x16x32_bf16 v[56:59], v[212:215], v[244:247], v[56:59]
	v_mfma_f32_16x16x32_bf16 v[60:63], v[214:217], v[244:247], v[60:63]
	v_mfma_f32_16x16x32_bf16 v[64:67], v[216:219], v[244:247], v[64:67]
	s_nop 1
	v_pk_mul_f32 v[84:85], v[84:85], v[228:229]
	v_pk_mul_f32 v[86:87], v[86:87], v[230:231]
	v_cvt_pk_bf16_f32 v88, v84, v85
	v_cvt_pk_bf16_f32 v90, v86, v87
	s_nop 1
	v_mov_b32_dpp v89, v88 quad_perm:[1,0,3,2] row_mask:0xf bank_mask:0xf
	v_mov_b32_dpp v91, v90 quad_perm:[1,0,3,2] row_mask:0xf bank_mask:0xf
	v_perm_b32 v88, v89, v88, v92
	v_perm_b32 v90, v91, v90, v92
	ds_write_b32 v93, v88 offset:13056
	ds_write_b32 v93, v90 offset:13600
	s_waitcnt lgkmcnt(0)
	s_barrier
	s_waitcnt lgkmcnt(0)
	s_cbranch_scc1 .LBB0_1021
